# attention exp sections: VALU->MFMA wait states filled with the following v_exp instead of s_nop (8 sites)
# baseline (speedup 1.0000x reference)
.LBB0_223:
	v_exp_f32_e32 v81, v48
	v_exp_f32_e32 v83, v49
	v_exp_f32_e32 v85, v50
	v_exp_f32_e32 v87, v51
	v_exp_f32_e32 v89, v52
	v_exp_f32_e32 v91, v53
	v_exp_f32_e32 v93, v54
	v_exp_f32_e32 v95, v55
	v_cvt_pk_bf16_f32 v48, v81, v83
	v_cvt_pk_bf16_f32 v49, v85, v87
	v_cvt_pk_bf16_f32 v50, v89, v91
	v_cvt_pk_bf16_f32 v51, v93, v95
	s_waitcnt lgkmcnt(14)
	v_exp_f32_e32 v97, v56
	v_mfma_f32_32x32x16_bf16 v[16:31], v[156:159], v[48:51], v[16:31]
	v_exp_f32_e32 v99, v57
	v_exp_f32_e32 v101, v58
	v_exp_f32_e32 v103, v59
	v_exp_f32_e32 v105, v60
	v_exp_f32_e32 v61, v61
	v_exp_f32_e32 v107, v62
	v_exp_f32_e32 v63, v63
	v_cvt_pk_bf16_f32 v52, v97, v99
	v_cvt_pk_bf16_f32 v53, v101, v103
	v_cvt_pk_bf16_f32 v54, v105, v61
	v_cvt_pk_bf16_f32 v55, v107, v63
	s_waitcnt lgkmcnt(12)
	v_exp_f32_e32 v80, v64
	v_mfma_f32_32x32x16_bf16 v[16:31], v[152:155], v[52:55], v[16:31]
	v_exp_f32_e32 v82, v65
	v_exp_f32_e32 v84, v66
	v_exp_f32_e32 v86, v67
	v_exp_f32_e32 v88, v68
	v_exp_f32_e32 v90, v69
	v_exp_f32_e32 v92, v70
	v_exp_f32_e32 v94, v71
	v_cvt_pk_bf16_f32 v56, v80, v82
	v_cvt_pk_bf16_f32 v57, v84, v86
	v_cvt_pk_bf16_f32 v58, v88, v90
	v_cvt_pk_bf16_f32 v59, v92, v94
	s_waitcnt lgkmcnt(10)
	v_mfma_f32_32x32x16_bf16 v[0:15], v[148:151], v[48:51], v[0:15]
	v_exp_f32_e32 v96, v72
	v_exp_f32_e32 v98, v73
	v_pk_add_f32 v[64:65], v[80:81], 0 op_sel_hi:[1,0]
	v_exp_f32_e32 v100, v74
	v_exp_f32_e32 v102, v75
	v_exp_f32_e32 v104, v76
	v_exp_f32_e32 v60, v77
	s_waitcnt lgkmcnt(8)
	v_mfma_f32_32x32x16_bf16 v[0:15], v[144:147], v[52:55], v[0:15]
	v_add_f32_e64 v52, v82, 0
	v_add_f32_e64 v53, v83, 0
	v_add_f32_e64 v54, v84, v64
	v_add_f32_e64 v55, v85, v65
	v_add_f32_e64 v52, v86, v52
	v_add_f32_e64 v53, v87, v53
	v_pk_add_f32 v[54:55], v[88:89], v[54:55]
	v_pk_add_f32 v[52:53], v[90:91], v[52:53]
	v_exp_f32_e32 v106, v78
	v_exp_f32_e32 v62, v79
	v_pk_add_f32 v[54:55], v[92:93], v[54:55]
	v_pk_add_f32 v[52:53], v[94:95], v[52:53]
	s_waitcnt lgkmcnt(6)
	v_mfma_f32_32x32x16_bf16 v[16:31], v[140:143], v[56:59], v[16:31]
	v_add_f32_e64 v54, v96, v54
	v_add_f32_e64 v55, v97, v55
	v_add_f32_e64 v52, v98, v52
	v_add_f32_e64 v53, v99, v53
	v_add_f32_e64 v54, v100, v54
	v_add_f32_e64 v55, v101, v55
	v_pk_add_f32 v[52:53], v[102:103], v[52:53]
	v_pk_add_f32 v[54:55], v[104:105], v[54:55]
	v_pk_add_f32 v[52:53], v[60:61], v[52:53]
	v_pk_add_f32 v[54:55], v[106:107], v[54:55]
	s_waitcnt lgkmcnt(2)
	v_mfma_f32_32x32x16_bf16 v[0:15], v[136:139], v[56:59], v[0:15]
	v_add_f32_e64 v52, v62, v52
	v_add_f32_e64 v53, v63, v53
	v_cvt_pk_bf16_f32 v48, v96, v98
	v_add_f32_e64 v52, v52, v54
	v_add_f32_e64 v53, v53, v55
	v_cvt_pk_bf16_f32 v49, v100, v102
	v_add_f32_e32 v52, v52, v53
	v_add_f32_e32 v161, v161, v52
	v_cvt_pk_bf16_f32 v50, v104, v60
	v_cvt_pk_bf16_f32 v51, v106, v62
	s_nop 1
	v_mfma_f32_32x32x16_bf16 v[16:31], v[128:131], v[48:51], v[16:31]
	s_waitcnt lgkmcnt(0)
	v_mfma_f32_32x32x16_bf16 v[0:15], v[132:135], v[48:51], v[0:15]

.LBB0_249:
	v_exp_f32_e32 v79, v138
	v_exp_f32_e32 v139, v139
	v_exp_f32_e32 v145, v136
	v_exp_f32_e32 v137, v137
	v_exp_f32_e32 v147, v68
	v_exp_f32_e32 v149, v69
	v_exp_f32_e32 v151, v70
	v_exp_f32_e32 v153, v71
	v_cvt_pk_bf16_f32 v68, v79, v139
	v_cvt_pk_bf16_f32 v69, v145, v137
	v_cvt_pk_bf16_f32 v70, v147, v149
	v_cvt_pk_bf16_f32 v71, v151, v153
	v_exp_f32_e32 v155, v72
	v_exp_f32_e32 v73, v73
	v_mfma_f32_32x32x16_bf16 v[16:31], v[124:127], v[68:71], v[16:31]
	v_exp_f32_e32 v157, v74
	v_exp_f32_e32 v75, v75
	v_exp_f32_e32 v159, v76
	v_exp_f32_e32 v77, v77
	v_exp_f32_e32 v163, v60
	v_exp_f32_e32 v165, v61
	v_cvt_pk_bf16_f32 v60, v155, v73
	v_cvt_pk_bf16_f32 v61, v157, v75
	v_cvt_pk_bf16_f32 v62, v159, v77
	v_cvt_pk_bf16_f32 v63, v163, v165
	v_exp_f32_e32 v78, v64
	v_exp_f32_e32 v138, v65
	v_mfma_f32_32x32x16_bf16 v[16:31], v[120:123], v[60:63], v[16:31]
	v_exp_f32_e32 v144, v48
	v_exp_f32_e32 v136, v49
	v_exp_f32_e32 v146, v50
	v_exp_f32_e32 v148, v51
	v_exp_f32_e32 v150, v66
	v_exp_f32_e32 v152, v67
	v_cvt_pk_bf16_f32 v48, v78, v138
	v_cvt_pk_bf16_f32 v49, v144, v136
	v_cvt_pk_bf16_f32 v50, v146, v148
	v_cvt_pk_bf16_f32 v51, v150, v152
	v_mfma_f32_32x32x16_bf16 v[0:15], v[116:119], v[68:71], v[0:15]
	v_exp_f32_e32 v154, v54
	v_exp_f32_e32 v72, v55
	v_exp_f32_e32 v158, v56
	v_exp_f32_e32 v76, v57
	v_exp_f32_e32 v162, v58
	v_exp_f32_e32 v164, v59
	v_pk_add_f32 v[56:57], v[78:79], 0 op_sel_hi:[1,0]
	v_mfma_f32_32x32x16_bf16 v[0:15], v[112:115], v[60:63], v[0:15]
	v_add_f32_e64 v58, v138, 0
	v_add_f32_e64 v59, v139, 0
	v_exp_f32_e32 v156, v52
	v_exp_f32_e32 v74, v53
	v_pk_add_f32 v[56:57], v[144:145], v[56:57]
	v_pk_add_f32 v[58:59], v[136:137], v[58:59]
	v_pk_add_f32 v[56:57], v[146:147], v[56:57]
	v_pk_add_f32 v[58:59], v[148:149], v[58:59]
	v_pk_add_f32 v[56:57], v[150:151], v[56:57]
	v_pk_add_f32 v[58:59], v[152:153], v[58:59]
	v_mfma_f32_32x32x16_bf16 v[16:31], v[108:111], v[48:51], v[16:31]
	v_add_f32_e64 v56, v154, v56
	v_add_f32_e64 v57, v155, v57
	v_add_f32_e64 v58, v72, v58
	v_add_f32_e64 v59, v73, v59
	v_add_f32_e64 v56, v156, v56
	v_add_f32_e64 v57, v157, v57
	v_pk_add_f32 v[58:59], v[74:75], v[58:59]
	v_pk_add_f32 v[56:57], v[158:159], v[56:57]
	v_pk_add_f32 v[58:59], v[76:77], v[58:59]
	v_pk_add_f32 v[56:57], v[162:163], v[56:57]
	v_mfma_f32_32x32x16_bf16 v[0:15], v[104:107], v[48:51], v[0:15]
	v_add_f32_e64 v48, v164, v58
	v_add_f32_e64 v49, v165, v59
	v_cvt_pk_bf16_f32 v52, v154, v72
	v_add_f32_e64 v48, v48, v56
	v_add_f32_e64 v49, v49, v57
	v_cvt_pk_bf16_f32 v53, v156, v74
	v_add_f32_e32 v48, v48, v49
	v_add_f32_e32 v143, v143, v48
	v_cvt_pk_bf16_f32 v54, v158, v76
	v_cvt_pk_bf16_f32 v55, v162, v164
	s_nop 1
	v_mfma_f32_32x32x16_bf16 v[16:31], v[96:99], v[52:55], v[16:31]
	v_mfma_f32_32x32x16_bf16 v[0:15], v[100:103], v[52:55], v[0:15]

.LBB0_283:
	v_exp_f32_e32 v77, v134
	v_exp_f32_e32 v79, v135
	v_exp_f32_e32 v135, v138
	v_exp_f32_e32 v139, v139
	v_exp_f32_e32 v151, v68
	v_exp_f32_e32 v153, v69
	v_exp_f32_e32 v155, v70
	v_exp_f32_e32 v157, v71
	v_cvt_pk_bf16_f32 v68, v77, v79
	v_cvt_pk_bf16_f32 v69, v135, v139
	v_cvt_pk_bf16_f32 v70, v151, v153
	v_cvt_pk_bf16_f32 v71, v155, v157
	s_waitcnt lgkmcnt(14)
	v_exp_f32_e32 v159, v72
	v_mfma_f32_32x32x16_bf16 v[16:31], v[124:127], v[68:71], v[16:31]
	v_exp_f32_e32 v73, v73
	v_exp_f32_e32 v161, v74
	v_exp_f32_e32 v75, v75
	v_exp_f32_e32 v163, v60
	v_exp_f32_e32 v165, v61
	v_exp_f32_e32 v167, v62
	v_exp_f32_e32 v169, v63
	v_cvt_pk_bf16_f32 v60, v159, v73
	v_cvt_pk_bf16_f32 v61, v161, v75
	v_cvt_pk_bf16_f32 v62, v163, v165
	v_cvt_pk_bf16_f32 v63, v167, v169
	s_waitcnt lgkmcnt(12)
	v_exp_f32_e32 v76, v48
	v_mfma_f32_32x32x16_bf16 v[16:31], v[120:123], v[60:63], v[16:31]
	v_exp_f32_e32 v78, v49
	v_exp_f32_e32 v134, v64
	v_exp_f32_e32 v138, v65
	v_exp_f32_e32 v150, v50
	v_exp_f32_e32 v152, v51
	v_exp_f32_e32 v154, v66
	v_exp_f32_e32 v156, v67
	v_cvt_pk_bf16_f32 v48, v76, v78
	v_cvt_pk_bf16_f32 v49, v134, v138
	v_cvt_pk_bf16_f32 v50, v150, v152
	v_cvt_pk_bf16_f32 v51, v154, v156
	s_waitcnt lgkmcnt(10)
	v_mfma_f32_32x32x16_bf16 v[0:15], v[116:119], v[68:71], v[0:15]
	v_exp_f32_e32 v158, v52
	v_exp_f32_e32 v72, v53
	v_exp_f32_e32 v162, v56
	v_exp_f32_e32 v164, v57
	v_exp_f32_e32 v166, v58
	v_exp_f32_e32 v168, v59
	v_pk_add_f32 v[56:57], v[76:77], 0 op_sel_hi:[1,0]
	s_waitcnt lgkmcnt(8)
	v_mfma_f32_32x32x16_bf16 v[0:15], v[112:115], v[60:63], v[0:15]
	v_add_f32_e64 v58, v78, 0
	v_add_f32_e64 v59, v79, 0
	v_exp_f32_e32 v160, v54
	v_exp_f32_e32 v74, v55
	v_pk_add_f32 v[56:57], v[134:135], v[56:57]
	v_pk_add_f32 v[58:59], v[138:139], v[58:59]
	v_pk_add_f32 v[56:57], v[150:151], v[56:57]
	v_pk_add_f32 v[58:59], v[152:153], v[58:59]
	v_pk_add_f32 v[56:57], v[154:155], v[56:57]
	v_pk_add_f32 v[58:59], v[156:157], v[58:59]
	s_waitcnt lgkmcnt(6)
	v_mfma_f32_32x32x16_bf16 v[16:31], v[108:111], v[48:51], v[16:31]
	v_add_f32_e64 v56, v158, v56
	v_add_f32_e64 v57, v159, v57
	v_add_f32_e64 v58, v72, v58
	v_add_f32_e64 v59, v73, v59
	v_add_f32_e64 v56, v160, v56
	v_add_f32_e64 v57, v161, v57
	v_pk_add_f32 v[58:59], v[74:75], v[58:59]
	v_pk_add_f32 v[56:57], v[162:163], v[56:57]
	v_pk_add_f32 v[58:59], v[164:165], v[58:59]
	v_pk_add_f32 v[56:57], v[166:167], v[56:57]
	s_waitcnt lgkmcnt(2)
	v_mfma_f32_32x32x16_bf16 v[0:15], v[104:107], v[48:51], v[0:15]
	v_add_f32_e64 v48, v168, v58
	v_add_f32_e64 v49, v169, v59
	v_cvt_pk_bf16_f32 v52, v158, v72
	v_add_f32_e64 v48, v48, v56
	v_add_f32_e64 v49, v49, v57
	v_cvt_pk_bf16_f32 v53, v160, v74
	v_add_f32_e32 v48, v48, v49
	v_add_f32_e32 v141, v141, v48
	v_cvt_pk_bf16_f32 v54, v162, v164
	v_cvt_pk_bf16_f32 v55, v166, v168
	s_nop 1
	v_mfma_f32_32x32x16_bf16 v[16:31], v[96:99], v[52:55], v[16:31]
	s_waitcnt lgkmcnt(0)
	v_mfma_f32_32x32x16_bf16 v[0:15], v[100:103], v[52:55], v[0:15]

.LBB0_304:
	v_exp_f32_e32 v151, v64
	v_exp_f32_e32 v153, v65
	v_exp_f32_e32 v155, v66
	v_exp_f32_e32 v157, v67
	v_exp_f32_e32 v159, v68
	v_exp_f32_e32 v161, v69
	v_exp_f32_e32 v163, v70
	v_exp_f32_e32 v165, v71
	v_cvt_pk_bf16_f32 v64, v151, v153
	v_cvt_pk_bf16_f32 v65, v155, v157
	v_cvt_pk_bf16_f32 v66, v159, v161
	v_cvt_pk_bf16_f32 v67, v163, v165
	s_waitcnt lgkmcnt(14)
	v_exp_f32_e32 v167, v72
	v_mfma_f32_32x32x16_bf16 v[16:31], v[132:135], v[64:67], v[16:31]
	v_exp_f32_e32 v73, v73
	v_exp_f32_e32 v169, v74
	v_exp_f32_e32 v75, v75
	v_exp_f32_e32 v171, v76
	v_exp_f32_e32 v77, v77
	v_exp_f32_e32 v173, v78
	v_exp_f32_e32 v79, v79
	v_cvt_pk_bf16_f32 v68, v167, v73
	v_cvt_pk_bf16_f32 v69, v169, v75
	v_cvt_pk_bf16_f32 v70, v171, v77
	v_cvt_pk_bf16_f32 v71, v173, v79
	s_waitcnt lgkmcnt(12)
	v_exp_f32_e32 v150, v48
	v_mfma_f32_32x32x16_bf16 v[16:31], v[128:131], v[68:71], v[16:31]
	v_exp_f32_e32 v152, v49
	v_exp_f32_e32 v154, v50
	v_exp_f32_e32 v156, v51
	v_exp_f32_e32 v158, v52
	v_exp_f32_e32 v160, v53
	v_exp_f32_e32 v162, v54
	v_exp_f32_e32 v164, v55
	v_cvt_pk_bf16_f32 v48, v150, v152
	v_cvt_pk_bf16_f32 v49, v154, v156
	v_cvt_pk_bf16_f32 v50, v158, v160
	v_cvt_pk_bf16_f32 v51, v162, v164
	s_waitcnt lgkmcnt(10)
	v_mfma_f32_32x32x16_bf16 v[0:15], v[124:127], v[64:67], v[0:15]
	v_exp_f32_e32 v166, v56
	v_exp_f32_e32 v72, v57
	v_exp_f32_e32 v168, v58
	v_exp_f32_e32 v74, v59
	v_pk_add_f32 v[56:57], v[150:151], 0 op_sel_hi:[1,0]
	v_pk_add_f32 v[58:59], v[152:153], 0 op_sel_hi:[1,0]
	v_pk_add_f32 v[56:57], v[154:155], v[56:57]
	s_waitcnt lgkmcnt(8)
	v_mfma_f32_32x32x16_bf16 v[0:15], v[120:123], v[68:71], v[0:15]
	v_add_f32_e64 v58, v156, v58
	v_add_f32_e64 v59, v157, v59
	v_exp_f32_e32 v170, v60
	v_exp_f32_e32 v76, v61
	v_pk_add_f32 v[56:57], v[158:159], v[56:57]
	v_pk_add_f32 v[58:59], v[160:161], v[58:59]
	v_exp_f32_e32 v172, v62
	v_exp_f32_e32 v78, v63
	v_pk_add_f32 v[56:57], v[162:163], v[56:57]
	v_pk_add_f32 v[58:59], v[164:165], v[58:59]
	s_waitcnt lgkmcnt(6)
	v_mfma_f32_32x32x16_bf16 v[16:31], v[116:119], v[48:51], v[16:31]
	v_add_f32_e64 v56, v166, v56
	v_add_f32_e64 v57, v167, v57
	v_add_f32_e64 v58, v72, v58
	v_add_f32_e64 v59, v73, v59
	v_add_f32_e64 v56, v168, v56
	v_add_f32_e64 v57, v169, v57
	v_pk_add_f32 v[58:59], v[74:75], v[58:59]
	v_pk_add_f32 v[56:57], v[170:171], v[56:57]
	v_pk_add_f32 v[58:59], v[76:77], v[58:59]
	v_pk_add_f32 v[56:57], v[172:173], v[56:57]
	s_waitcnt lgkmcnt(2)
	v_mfma_f32_32x32x16_bf16 v[0:15], v[112:115], v[48:51], v[0:15]
	v_add_f32_e64 v48, v78, v58
	v_add_f32_e64 v49, v79, v59
	v_cvt_pk_bf16_f32 v52, v166, v72
	v_add_f32_e64 v48, v48, v56
	v_add_f32_e64 v49, v49, v57
	v_cvt_pk_bf16_f32 v53, v168, v74
	v_add_f32_e32 v48, v48, v49
	v_add_f32_e32 v148, v148, v48
	v_cvt_pk_bf16_f32 v54, v170, v76
	v_cvt_pk_bf16_f32 v55, v172, v78
	s_nop 1
	v_mfma_f32_32x32x16_bf16 v[16:31], v[104:107], v[52:55], v[16:31]
	s_waitcnt lgkmcnt(0)
	v_mfma_f32_32x32x16_bf16 v[0:15], v[108:111], v[52:55], v[0:15]
